# diff-attention softmax row sums: 16-long v_add_f32 chains replaced by v_pk_add_f32 trees (f32, 7 packed adds + 1) on top of the session best
# baseline (speedup 1.0000x reference)
; DI int ltid() { int t = threadIdx.x; asm volatile("" : "+v"(t)); return t; }
; #define store_tile() do { \
;     *reinterpret_cast<uint4*>(kdst0) = kreg0; *reinterpret_cast<uint4*>(kdst1) = kreg1; \
;     *reinterpret_cast<uint4*>(vdst0) = vreg0; *reinterpret_cast<uint4*>(vdst1) = vreg1; } while (0)
;   DI void tile(const u16* Ks, const u16* Vts) {
;     ...
;     const int lane = ltid() & 63, fr = lane & 15, fq = lane >> 4;
;     float base[NQB];
; #pragma unroll
;     for (int qb = 0; qb < NQB; ++qb) base[qb] = (m[qb] == -INFINITY) ? 0.f : m[qb];
;     f32x4 s[4][NQB];
;     __builtin_amdgcn_s_setprio(1);
; #pragma unroll
;     for (int kb = 0; kb < 4; ++kb) {
; #pragma unroll
;       for (int qb = 0; qb < NQB; ++qb) s[kb][qb] = f32x4{-base[qb], -base[qb], -base[qb], -base[qb]};
; #pragma unroll
;       for (int ks = 0; ks < DK / 32; ++ks) {
;         bf16x8 kf = *reinterpret_cast<const bf16x8*>(Ks + (kb * 16 + fr) * KSTR + ks * 32 + fq * 8);
; #pragma unroll
;         for (int qb = 0; qb < NQB; ++qb) s[kb][qb] = __builtin_amdgcn_mfma_f32_16x16x32_bf16(kf, qf[qb][ks], s[kb][qb], 0, 0, 0);
;       }
;     }
;     __builtin_amdgcn_s_setprio(0);
;     bf16x8 pf[NQB][2];
; #pragma unroll
;     for (int qb = 0; qb < NQB; ++qb) {
;       float mx = -INFINITY;
; #pragma unroll
;       for (int kb = 0; kb < 4; ++kb) {
; #pragma unroll
;         for (int j = 0; j < 4; ++j) mx = fmaxf(mx, s[kb][qb][j]); }
;       mx = fmaxf(mx, __shfl_xor(mx, 16));
;       mx = fmaxf(mx, __shfl_xor(mx, 32));
;       const float mn = fmaxf(m[qb], base[qb] + mx);
;       const bool changed = __any(mn > m[qb]);
;       float sum = 0.f;
;       if (changed) {
;         const float delta = mn - base[qb];
;         const float alpha = __builtin_amdgcn_exp2f(m[qb] - mn);
; #pragma unroll
;         for (int kb = 0; kb < 4; ++kb) {
; #pragma unroll
;           for (int j = 0; j < 4; ++j) { float e = __builtin_amdgcn_exp2f(s[kb][qb][j] - delta); s[kb][qb][j] = e; sum += e; } }
;         l[qb] = l[qb] * alpha + sum;
; DI void diff_attn_item(const PRef& p, int l, int b, int h, int qt) {
;     ...
;   for (int kt = 0; kt < nkt; ++kt) {
;     __syncthreads();
;     store_tile();
;     __syncthreads();
;     if (kt + 1 < nkt) load_tile(kt + 1);
;     if (kt <= my_last) fw.tile(Ks + n * 64 * 72, Vts);
.LBB0_198:
	v_cmp_le_u32_e32 vcc, s6, v193
	s_and_saveexec_b64 s[6:7], vcc
	s_cbranch_execz .LBB0_206
	v_cmp_neq_f32_e32 vcc, s42, v115
	v_mov_b32_e32 v98, v234
	s_nop 0
	v_cndmask_b32_e32 v114, 0, v115, vcc
	v_cmp_neq_f32_e32 vcc, s42, v202
	v_and_b32_e32 v99, 15, v98
	s_nop 0
	v_cndmask_b32_e32 v205, 0, v202, vcc
	s_setprio 1
	v_lshrrev_b32_e32 v98, 1, v98
	v_and_b32_e32 v198, 24, v98
	v_lshlrev_b32_e32 v98, 1, v198
	v_mul_u32_u24_e32 v200, 0x90, v99
	v_add3_u32 v128, v196, v98, v200
	ds_read_b128 v[208:211], v128
	ds_read_b128 v[212:215], v128 offset:64
	ds_read_b128 v[216:219], v128 offset:2304
	ds_read_b128 v[220:223], v128 offset:2368
	ds_read_b128 v[224:227], v128 offset:4608
	ds_read_b128 v[124:127], v128 offset:4672
	v_xor_b32_e32 v110, 0x80000000, v114
	v_mov_b32_e32 v111, v110
	v_mov_b32_e32 v112, v110
	v_mov_b32_e32 v113, v110
	v_xor_b32_e32 v116, 0x80000000, v205
	v_mov_b32_e32 v117, v116
	v_mov_b32_e32 v118, v116
	v_mov_b32_e32 v119, v116
	s_waitcnt lgkmcnt(5)
	v_mfma_f32_16x16x32_bf16 v[102:105], v[208:211], v[34:37], v[110:113]
	s_waitcnt lgkmcnt(4)
	v_mfma_f32_16x16x32_bf16 v[162:165], v[212:215], v[38:41], v[102:105]
	v_mfma_f32_16x16x32_bf16 v[98:101], v[208:211], v[42:45], v[116:119]
	v_mfma_f32_16x16x32_bf16 v[98:101], v[212:215], v[46:49], v[98:101]
	ds_read_b128 v[208:211], v128 offset:6912
	ds_read_b128 v[212:215], v128 offset:6976
	s_waitcnt lgkmcnt(5)
	v_mfma_f32_16x16x32_bf16 v[106:109], v[216:219], v[34:37], v[110:113]
	s_waitcnt lgkmcnt(4)
	v_mfma_f32_16x16x32_bf16 v[166:169], v[220:223], v[38:41], v[106:109]
	v_mfma_f32_16x16x32_bf16 v[102:105], v[216:219], v[42:45], v[116:119]
	v_mfma_f32_16x16x32_bf16 v[102:105], v[220:223], v[46:49], v[102:105]
	s_waitcnt lgkmcnt(3)
	v_mfma_f32_16x16x32_bf16 v[120:123], v[224:227], v[34:37], v[110:113]
	s_waitcnt lgkmcnt(2)
	v_mfma_f32_16x16x32_bf16 v[170:173], v[124:127], v[38:41], v[120:123]
	v_mfma_f32_16x16x32_bf16 v[106:109], v[224:227], v[42:45], v[116:119]
	s_waitcnt lgkmcnt(1)
	v_mfma_f32_16x16x32_bf16 v[110:113], v[208:211], v[34:37], v[110:113]
	v_mfma_f32_16x16x32_bf16 v[116:119], v[208:211], v[42:45], v[116:119]
	v_mfma_f32_16x16x32_bf16 v[106:109], v[124:127], v[46:49], v[106:109]
	s_waitcnt lgkmcnt(0)
	v_mfma_f32_16x16x32_bf16 v[174:177], v[212:215], v[38:41], v[110:113]
	v_mfma_f32_16x16x32_bf16 v[110:113], v[212:215], v[46:49], v[116:119]
	s_setprio 0
	s_nop 1
	v_and_b32_e32 v117, 64, v239
	v_xor_b32_e32 v116, 16, v239
	v_add_u32_e32 v117, 64, v117
	v_cmp_lt_i32_e32 vcc, v116, v117
	v_xor_b32_e32 v119, 32, v239
	s_nop 0
	v_cndmask_b32_e32 v116, v239, v116, vcc
	v_lshlrev_b32_e32 v204, 2, v116
	v_max3_f32 v116, v162, s42, v163
	v_max3_f32 v116, v116, v164, v165
	v_max3_f32 v116, v116, v166, v167
	v_max3_f32 v116, v116, v168, v169
	v_max3_f32 v116, v116, v170, v171
	v_max3_f32 v116, v116, v172, v173
	v_max3_f32 v116, v116, v174, v175
	v_max3_f32 v116, v116, v176, v177
	ds_bpermute_b32 v118, v204, v116
	v_cmp_lt_i32_e32 vcc, v119, v117
	s_nop 1
	v_cndmask_b32_e32 v117, v239, v119, vcc
	v_lshlrev_b32_e32 v206, 2, v117
	s_waitcnt lgkmcnt(0)
	v_max_f32_e32 v117, v118, v118
	v_max_f32_e32 v116, v116, v117
	ds_bpermute_b32 v117, v206, v116
	s_waitcnt lgkmcnt(0)
	v_max_f32_e32 v117, v117, v117
	v_max_f32_e32 v116, v116, v117
	v_add_f32_e32 v116, v114, v116
	v_max_f32_e32 v117, v115, v115
	v_max_f32_e32 v199, v117, v116
	v_cmp_gt_f32_e32 vcc, v199, v115
	s_cbranch_vccz .LBB0_208
	v_sub_f32_e32 v129, v199, v114
	v_sub_f32_e32 v114, v162, v129
	v_exp_f32_e32 v114, v114
	v_sub_f32_e32 v130, v115, v199
	v_sub_f32_e32 v115, v163, v129
	v_exp_f32_e32 v115, v115
	v_sub_f32_e32 v116, v164, v129
	v_exp_f32_e32 v116, v116
	v_sub_f32_e32 v117, v165, v129
	v_exp_f32_e32 v117, v117
	v_sub_f32_e32 v118, v166, v129
	v_exp_f32_e32 v118, v118
	v_sub_f32_e32 v119, v167, v129
	v_exp_f32_e32 v119, v119
	v_sub_f32_e32 v120, v168, v129
	v_exp_f32_e32 v120, v120
	v_sub_f32_e32 v121, v169, v129
	v_exp_f32_e32 v121, v121
	v_sub_f32_e32 v122, v170, v129
	v_exp_f32_e32 v122, v122
	v_sub_f32_e32 v123, v171, v129
	v_exp_f32_e32 v123, v123
	v_sub_f32_e32 v124, v172, v129
	v_exp_f32_e32 v124, v124
	v_sub_f32_e32 v125, v173, v129
	v_exp_f32_e32 v125, v125
	v_sub_f32_e32 v126, v174, v129
	v_exp_f32_e32 v126, v126
	v_sub_f32_e32 v127, v175, v129
	v_exp_f32_e32 v127, v127
	v_sub_f32_e32 v128, v176, v129
	v_exp_f32_e32 v128, v128
	v_sub_f32_e32 v129, v177, v129
	v_exp_f32_e32 v129, v129
	v_exp_f32_e32 v130, v130
	v_pk_add_f32 v[208:209], v[114:115], v[116:117]
	v_pk_add_f32 v[210:211], v[118:119], v[120:121]
	v_pk_add_f32 v[212:213], v[122:123], v[124:125]
	v_pk_add_f32 v[208:209], v[208:209], v[210:211]
	v_pk_add_f32 v[210:211], v[126:127], v[128:129]
	v_pk_add_f32 v[208:209], v[208:209], v[212:213]
	s_nop 0
	v_pk_add_f32 v[208:209], v[208:209], v[210:211]
	s_nop 0
	v_add_f32_e32 v203, v208, v209
	v_fmac_f32_e32 v203, v201, v130
	v_pk_mul_f32 v[160:161], v[68:69], v[130:131] op_sel_hi:[1,0]
	v_pk_mul_f32 v[158:159], v[66:67], v[130:131] op_sel_hi:[1,0]
	v_pk_mul_f32 v[156:157], v[72:73], v[130:131] op_sel_hi:[1,0]
	v_pk_mul_f32 v[154:155], v[70:71], v[130:131] op_sel_hi:[1,0]
	v_pk_mul_f32 v[152:153], v[76:77], v[130:131] op_sel_hi:[1,0]
	v_pk_mul_f32 v[150:151], v[74:75], v[130:131] op_sel_hi:[1,0]
	v_pk_mul_f32 v[148:149], v[80:81], v[130:131] op_sel_hi:[1,0]
	v_pk_mul_f32 v[146:147], v[78:79], v[130:131] op_sel_hi:[1,0]
	v_pk_mul_f32 v[144:145], v[84:85], v[130:131] op_sel_hi:[1,0]
	v_pk_mul_f32 v[142:143], v[82:83], v[130:131] op_sel_hi:[1,0]
	v_pk_mul_f32 v[140:141], v[92:93], v[130:131] op_sel_hi:[1,0]
	v_pk_mul_f32 v[138:139], v[90:91], v[130:131] op_sel_hi:[1,0]
	v_pk_mul_f32 v[136:137], v[88:89], v[130:131] op_sel_hi:[1,0]
	v_pk_mul_f32 v[134:135], v[86:87], v[130:131] op_sel_hi:[1,0]
	v_pk_mul_f32 v[132:133], v[96:97], v[130:131] op_sel_hi:[1,0]
	v_pk_mul_f32 v[130:131], v[94:95], v[130:131] op_sel_hi:[1,0]
	s_cbranch_execnz .LBB0_202
;   DI void tile(const u16* Ks, const u16* Vts) {
;     ...
;     for (int qb = 0; qb < NQB; ++qb) {
;       float mx = -INFINITY;
; #pragma unroll
;       for (int kb = 0; kb < 4; ++kb) {
; #pragma unroll
;         for (int j = 0; j < 4; ++j) mx = fmaxf(mx, s[kb][qb][j]); }
;       mx = fmaxf(mx, __shfl_xor(mx, 16));
;       mx = fmaxf(mx, __shfl_xor(mx, 32));
;       const float mn = fmaxf(m[qb], base[qb] + mx);
;       const bool changed = __any(mn > m[qb]);
;       float sum = 0.f;
;       if (changed) {
;         const float delta = mn - base[qb];
;         const float alpha = __builtin_amdgcn_exp2f(m[qb] - mn);
; #pragma unroll
;         for (int kb = 0; kb < 4; ++kb) {
; #pragma unroll
;           for (int j = 0; j < 4; ++j) { float e = __builtin_amdgcn_exp2f(s[kb][qb][j] - delta); s[kb][qb][j] = e; sum += e; } }
;         l[qb] = l[qb] * alpha + sum;
; #pragma unroll
;         for (int d = 0; d < DV / 16; ++d) { o[qb][d][0] *= alpha; o[qb][d][1] *= alpha; o[qb][d][2] *= alpha; o[qb][d][3] *= alpha; }
;       } else {
; #pragma unroll
;         for (int kb = 0; kb < 4; ++kb) {
; #pragma unroll
;           for (int j = 0; j < 4; ++j) { float e = __builtin_amdgcn_exp2f(s[kb][qb][j]); s[kb][qb][j] = e; sum += e; } }
;         l[qb] += sum;
;       }
;       m[qb] = mn;
.LBB0_201:
	v_exp_f32_e32 v114, v162
	v_exp_f32_e32 v115, v163
	v_exp_f32_e32 v116, v164
	v_exp_f32_e32 v117, v165
	v_exp_f32_e32 v118, v166
	v_exp_f32_e32 v119, v167
	v_exp_f32_e32 v120, v168
	v_exp_f32_e32 v121, v169
	v_exp_f32_e32 v122, v170
	v_exp_f32_e32 v123, v171
	v_exp_f32_e32 v124, v172
	v_exp_f32_e32 v125, v173
	v_exp_f32_e32 v126, v174
	v_exp_f32_e32 v127, v175
	v_exp_f32_e32 v128, v176
	v_exp_f32_e32 v129, v177
	v_pk_add_f32 v[208:209], v[114:115], v[116:117]
	v_pk_add_f32 v[210:211], v[118:119], v[120:121]
	v_pk_add_f32 v[212:213], v[122:123], v[124:125]
	v_pk_add_f32 v[208:209], v[208:209], v[210:211]
	v_pk_add_f32 v[210:211], v[126:127], v[128:129]
	v_pk_add_f32 v[208:209], v[208:209], v[212:213]
	s_nop 0
	v_pk_add_f32 v[208:209], v[208:209], v[210:211]
	s_nop 0
	v_add_f32_e32 v208, v208, v209
	v_add_f32_e32 v203, v201, v208
	v_mov_b64_e32 v[132:133], v[96:97]
	v_mov_b64_e32 v[136:137], v[88:89]
	v_mov_b64_e32 v[140:141], v[92:93]
	v_mov_b64_e32 v[144:145], v[84:85]
	v_mov_b64_e32 v[148:149], v[80:81]
	v_mov_b64_e32 v[152:153], v[76:77]
	v_mov_b64_e32 v[156:157], v[72:73]
	v_mov_b64_e32 v[160:161], v[68:69]
	v_mov_b64_e32 v[130:131], v[94:95]
	v_mov_b64_e32 v[134:135], v[86:87]
	v_mov_b64_e32 v[138:139], v[90:91]
	v_mov_b64_e32 v[142:143], v[82:83]
	v_mov_b64_e32 v[146:147], v[78:79]
	v_mov_b64_e32 v[150:151], v[74:75]
	v_mov_b64_e32 v[154:155], v[70:71]
	v_mov_b64_e32 v[158:159], v[66:67]
.LBB0_202:
	v_max3_f32 v66, v98, s42, v99
	v_max3_f32 v66, v66, v100, v101
	v_max3_f32 v66, v66, v102, v103
	v_max3_f32 v66, v66, v104, v105
	v_max3_f32 v66, v66, v106, v107
	v_max3_f32 v66, v66, v108, v109
	v_max3_f32 v66, v66, v110, v111
	v_max3_f32 v66, v66, v112, v113
	ds_bpermute_b32 v67, v204, v66
	s_waitcnt lgkmcnt(0)
	v_max_f32_e32 v67, v67, v67
	v_max_f32_e32 v66, v66, v67
	ds_bpermute_b32 v67, v206, v66
	s_waitcnt lgkmcnt(0)
	v_max_f32_e32 v67, v67, v67
	v_max_f32_e32 v66, v66, v67
	v_add_f32_e32 v66, v205, v66
	v_max_f32_e32 v67, v202, v202
	v_max_f32_e32 v204, v67, v66
	v_cmp_gt_f32_e32 vcc, v204, v202
	s_cbranch_vccz .LBB0_209
	v_sub_f32_e32 v81, v204, v205
	v_sub_f32_e32 v66, v98, v81
	v_exp_f32_e32 v66, v66
	v_sub_f32_e32 v67, v99, v81
	v_exp_f32_e32 v67, v67
	v_sub_f32_e32 v68, v100, v81
	v_exp_f32_e32 v68, v68
	v_sub_f32_e32 v69, v101, v81
	v_exp_f32_e32 v69, v69
	v_sub_f32_e32 v70, v102, v81
	v_exp_f32_e32 v70, v70
	v_sub_f32_e32 v71, v103, v81
	v_exp_f32_e32 v71, v71
	v_sub_f32_e32 v72, v104, v81
	v_exp_f32_e32 v72, v72
	v_sub_f32_e32 v73, v105, v81
	v_exp_f32_e32 v73, v73
	v_sub_f32_e32 v74, v106, v81
	v_exp_f32_e32 v74, v74
	v_sub_f32_e32 v75, v107, v81
	v_exp_f32_e32 v75, v75
	v_sub_f32_e32 v76, v108, v81
	v_exp_f32_e32 v76, v76
	v_sub_f32_e32 v77, v109, v81
	v_exp_f32_e32 v77, v77
	v_sub_f32_e32 v78, v110, v81
	v_exp_f32_e32 v78, v78
	v_sub_f32_e32 v79, v111, v81
	v_exp_f32_e32 v79, v79
	v_sub_f32_e32 v80, v112, v81
	v_exp_f32_e32 v80, v80
	v_sub_f32_e32 v81, v113, v81
	v_sub_f32_e32 v82, v202, v204
	v_exp_f32_e32 v81, v81
	v_exp_f32_e32 v82, v82
	v_pk_add_f32 v[208:209], v[66:67], v[68:69]
	v_pk_add_f32 v[210:211], v[70:71], v[72:73]
	v_pk_add_f32 v[212:213], v[74:75], v[76:77]
	v_pk_add_f32 v[208:209], v[208:209], v[210:211]
	v_pk_add_f32 v[210:211], v[78:79], v[80:81]
	v_pk_add_f32 v[208:209], v[208:209], v[212:213]
	s_nop 0
	v_pk_add_f32 v[208:209], v[208:209], v[210:211]
	s_nop 0
	v_add_f32_e32 v201, v208, v209
	v_fmac_f32_e32 v201, v197, v82
	v_pk_mul_f32 v[176:177], v[2:3], v[82:83] op_sel_hi:[1,0]
	v_pk_mul_f32 v[174:175], v[0:1], v[82:83] op_sel_hi:[1,0]
	v_pk_mul_f32 v[172:173], v[20:21], v[82:83] op_sel_hi:[1,0]
	v_pk_mul_f32 v[170:171], v[18:19], v[82:83] op_sel_hi:[1,0]
	v_pk_mul_f32 v[168:169], v[24:25], v[82:83] op_sel_hi:[1,0]
	v_pk_mul_f32 v[166:167], v[22:23], v[82:83] op_sel_hi:[1,0]
	v_pk_mul_f32 v[164:165], v[14:15], v[82:83] op_sel_hi:[1,0]
	v_pk_mul_f32 v[162:163], v[12:13], v[82:83] op_sel_hi:[1,0]
	v_pk_mul_f32 v[96:97], v[10:11], v[82:83] op_sel_hi:[1,0]
	v_pk_mul_f32 v[94:95], v[8:9], v[82:83] op_sel_hi:[1,0]
	v_pk_mul_f32 v[92:93], v[6:7], v[82:83] op_sel_hi:[1,0]
	v_pk_mul_f32 v[90:91], v[4:5], v[82:83] op_sel_hi:[1,0]
	v_pk_mul_f32 v[88:89], v[28:29], v[82:83] op_sel_hi:[1,0]
	v_pk_mul_f32 v[86:87], v[26:27], v[82:83] op_sel_hi:[1,0]
	v_pk_mul_f32 v[84:85], v[32:33], v[82:83] op_sel_hi:[1,0]
	v_pk_mul_f32 v[82:83], v[30:31], v[82:83] op_sel_hi:[1,0]
	s_cbranch_execnz .LBB0_205
.LBB0_204:
	v_exp_f32_e32 v66, v98
	v_exp_f32_e32 v67, v99
	v_exp_f32_e32 v68, v100
	v_exp_f32_e32 v69, v101
	v_exp_f32_e32 v70, v102
	v_exp_f32_e32 v71, v103
	v_exp_f32_e32 v72, v104
	v_exp_f32_e32 v73, v105
	v_exp_f32_e32 v74, v106
	v_exp_f32_e32 v75, v107
	v_exp_f32_e32 v76, v108
	v_exp_f32_e32 v77, v109
	v_exp_f32_e32 v78, v110
	v_exp_f32_e32 v79, v111
	v_exp_f32_e32 v80, v112
	v_exp_f32_e32 v81, v113
	v_pk_add_f32 v[208:209], v[66:67], v[68:69]
	v_pk_add_f32 v[210:211], v[70:71], v[72:73]
	v_pk_add_f32 v[212:213], v[74:75], v[76:77]
	v_pk_add_f32 v[208:209], v[208:209], v[210:211]
	v_pk_add_f32 v[210:211], v[78:79], v[80:81]
	v_pk_add_f32 v[208:209], v[208:209], v[212:213]
	s_nop 0
	v_pk_add_f32 v[208:209], v[208:209], v[210:211]
	s_nop 0
	v_add_f32_e32 v208, v208, v209
	v_add_f32_e32 v201, v197, v208
	v_mov_b64_e32 v[92:93], v[6:7]
	v_mov_b64_e32 v[96:97], v[10:11]
	v_mov_b64_e32 v[164:165], v[14:15]
	v_mov_b64_e32 v[168:169], v[24:25]
	v_mov_b64_e32 v[172:173], v[20:21]
	v_mov_b64_e32 v[176:177], v[2:3]
	v_mov_b64_e32 v[88:89], v[28:29]
	v_mov_b64_e32 v[84:85], v[32:33]
	v_mov_b64_e32 v[90:91], v[4:5]
	v_mov_b64_e32 v[94:95], v[8:9]
	v_mov_b64_e32 v[162:163], v[12:13]
	v_mov_b64_e32 v[166:167], v[22:23]
	v_mov_b64_e32 v[170:171], v[18:19]
	v_mov_b64_e32 v[174:175], v[0:1]
	v_mov_b64_e32 v[86:87], v[26:27]
	v_mov_b64_e32 v[82:83], v[30:31]
